# strategy 7.4 other half: one static s_setprio 1 for waves 0-3 before each GEMM K-loop, per-cluster flips deleted
# speedup vs baseline: 1.0095x; 1.0085x over previous
; template <class Epi>
; __device__ __forceinline__ void gemm_phase(LAS unsigned char* lds, const Gemm g, const StaticOrder& S, const Epi& E) {
;     ...
;         const bool has_next = S.next(ui + 1, nxt);
;         const char* nA = has_next ? (const char*)g.A + (size_t)nxt.pm * tstepA : cA; const char* nB = has_next ? (const char*)g.Bt + (size_t)nxt.pn * tstepB : cB;
;         for (int t = 0; t < nt; t += 2) {
;     ...
; #pragma unroll
;         for (int a = 0; a < 2; ++a)
; #pragma unroll
;             for (int b = 0; b < 2; ++b)
; #pragma unroll
;                 for (int m = 0; m < 4; ++m)
; #pragma unroll
;                     for (int n = 0; n < 2; ++n) acc[a][b][m][n] = (f32x4){0.f, 0.f, 0.f, 0.f};
;         cur = nxt; cA = nA; cB = nB; ++ui;
.LBB0_139:
	s_add_u32 s93, s6, 0x100
	s_addc_u32 s94, s7, 0
	v_readlane_b32 s36, v254, 43
	s_add_u32 s6, s22, 0x80
	v_mov_b32_e32 v0, 0
	v_readlane_b32 s44, v254, 51
	v_readlane_b32 s45, v254, 52
	s_addc_u32 s7, s23, 0
	s_mov_b32 s22, 0
	v_mov_b32_e32 v1, v0
	v_mov_b32_e32 v2, v0
	v_mov_b32_e32 v3, v0
	v_mov_b32_e32 v4, v0
	v_mov_b32_e32 v5, v0
	v_mov_b32_e32 v6, v0
	v_mov_b32_e32 v7, v0
	v_mov_b32_e32 v16, v0
	v_mov_b32_e32 v17, v0
	v_mov_b32_e32 v18, v0
	v_mov_b32_e32 v19, v0
	v_mov_b32_e32 v20, v0
	v_mov_b32_e32 v21, v0
	v_mov_b32_e32 v22, v0
	v_mov_b32_e32 v23, v0
	v_mov_b32_e32 v34, v0
	v_mov_b32_e32 v35, v0
	v_mov_b32_e32 v36, v0
	v_mov_b32_e32 v37, v0
	v_mov_b32_e32 v38, v0
	v_mov_b32_e32 v39, v0
	v_mov_b32_e32 v40, v0
	v_mov_b32_e32 v41, v0
	v_mov_b32_e32 v50, v0
	v_mov_b32_e32 v51, v0
	v_mov_b32_e32 v52, v0
	v_mov_b32_e32 v53, v0
	v_mov_b32_e32 v54, v0
	v_mov_b32_e32 v55, v0
	v_mov_b32_e32 v56, v0
	v_mov_b32_e32 v57, v0
	v_mov_b32_e32 v8, v0
	v_mov_b32_e32 v9, v0
	v_mov_b32_e32 v10, v0
	v_mov_b32_e32 v11, v0
	v_mov_b32_e32 v12, v0
	v_mov_b32_e32 v13, v0
	v_mov_b32_e32 v14, v0
	v_mov_b32_e32 v15, v0
	v_mov_b32_e32 v24, v0
	v_mov_b32_e32 v25, v0
	v_mov_b32_e32 v26, v0
	v_mov_b32_e32 v27, v0
	v_mov_b32_e32 v28, v0
	v_mov_b32_e32 v29, v0
	v_mov_b32_e32 v30, v0
	v_mov_b32_e32 v31, v0
	v_mov_b32_e32 v42, v0
	v_mov_b32_e32 v43, v0
	v_mov_b32_e32 v44, v0
	v_mov_b32_e32 v45, v0
	v_mov_b32_e32 v46, v0
	v_mov_b32_e32 v47, v0
	v_mov_b32_e32 v48, v0
	v_mov_b32_e32 v49, v0
	v_mov_b32_e32 v58, v0
	v_mov_b32_e32 v59, v0
	v_mov_b32_e32 v60, v0
	v_mov_b32_e32 v61, v0
	v_mov_b32_e32 v62, v0
	v_mov_b32_e32 v63, v0
	v_mov_b32_e32 v64, v0
	v_mov_b32_e32 v65, v0
	v_mov_b32_e32 v66, v0
	v_mov_b32_e32 v67, v0
	v_mov_b32_e32 v68, v0
	v_mov_b32_e32 v69, v0
	v_mov_b32_e32 v70, v0
	v_mov_b32_e32 v71, v0
	v_mov_b32_e32 v72, v0
	v_mov_b32_e32 v73, v0
	v_mov_b32_e32 v82, v0
	v_mov_b32_e32 v83, v0
	v_mov_b32_e32 v84, v0
	v_mov_b32_e32 v85, v0
	v_mov_b32_e32 v86, v0
	v_mov_b32_e32 v87, v0
	v_mov_b32_e32 v88, v0
	v_mov_b32_e32 v89, v0
	v_mov_b32_e32 v98, v0
	v_mov_b32_e32 v99, v0
	v_mov_b32_e32 v100, v0
	v_mov_b32_e32 v101, v0
	v_mov_b32_e32 v102, v0
	v_mov_b32_e32 v103, v0
	v_mov_b32_e32 v104, v0
	v_mov_b32_e32 v105, v0
	v_mov_b32_e32 v114, v0
	v_mov_b32_e32 v115, v0
	v_mov_b32_e32 v116, v0
	v_mov_b32_e32 v117, v0
	v_mov_b32_e32 v118, v0
	v_mov_b32_e32 v119, v0
	v_mov_b32_e32 v120, v0
	v_mov_b32_e32 v121, v0
	v_mov_b32_e32 v74, v0
	v_mov_b32_e32 v75, v0
	v_mov_b32_e32 v76, v0
	v_mov_b32_e32 v77, v0
	v_mov_b32_e32 v78, v0
	v_mov_b32_e32 v79, v0
	v_mov_b32_e32 v80, v0
	v_mov_b32_e32 v81, v0
	v_mov_b32_e32 v90, v0
	v_mov_b32_e32 v91, v0
	v_mov_b32_e32 v92, v0
	v_mov_b32_e32 v93, v0
	v_mov_b32_e32 v94, v0
	v_mov_b32_e32 v95, v0
	v_mov_b32_e32 v96, v0
	v_mov_b32_e32 v97, v0
	v_mov_b32_e32 v106, v0
	v_mov_b32_e32 v107, v0
	v_mov_b32_e32 v108, v0
	v_mov_b32_e32 v109, v0
	v_mov_b32_e32 v110, v0
	v_mov_b32_e32 v111, v0
	v_mov_b32_e32 v112, v0
	v_mov_b32_e32 v113, v0
	v_mov_b32_e32 v122, v0
	v_mov_b32_e32 v123, v0
	v_mov_b32_e32 v124, v0
	v_mov_b32_e32 v125, v0
	v_mov_b32_e32 v126, v0
	v_mov_b32_e32 v127, v0
	v_mov_b32_e32 v128, v0
	v_mov_b32_e32 v129, v0
	s_mov_b64 s[24:25], s[44:45]
	v_readlane_b32 s37, v254, 44
	v_readlane_b32 s38, v254, 45
	v_readlane_b32 s39, v254, 46
	v_readlane_b32 s40, v254, 47
	v_readlane_b32 s41, v254, 48
	v_readlane_b32 s42, v254, 49
	v_readlane_b32 s43, v254, 50
	v_readlane_b32 s46, v254, 53
	v_readlane_b32 s47, v254, 54
	v_readlane_b32 s48, v254, 55
	v_readlane_b32 s49, v254, 56
	v_readlane_b32 s50, v254, 57
	v_readlane_b32 s51, v254, 58
	s_cmp_eq_u64 s[18:19], 0
	s_cbranch_scc1 .Lprio_140
	s_setprio 1

; template <class Epi>
; __device__ __forceinline__ void gemm_phase(LAS unsigned char* lds, const Gemm g, const StaticOrder& S, const Epi& E) {
;     ...
;         const bool has_next = S.next(ui + 1, nxt);
;         const char* nA = has_next ? (const char*)g.A + (size_t)nxt.pm * tstepA : cA; const char* nB = has_next ? (const char*)g.Bt + (size_t)nxt.pn * tstepB : cB;
;         for (int t = 0; t < nt; t += 2) {
;     ...
; #pragma unroll
;         for (int a = 0; a < 2; ++a)
; #pragma unroll
;             for (int b = 0; b < 2; ++b)
; #pragma unroll
;                 for (int m = 0; m < 4; ++m)
; #pragma unroll
;                     for (int n = 0; n < 2; ++n) acc[a][b][m][n] = (f32x4){0.f, 0.f, 0.f, 0.f};
;         cur = nxt; cA = nA; cB = nB; ++ui;
.LBB0_213:
	s_ashr_i32 s13, s12, 31
	s_lshl_b64 s[14:15], s[12:13], 19
	s_add_u32 s14, s84, s14
	s_addc_u32 s15, s85, s15
	s_and_b64 s[16:17], s[4:5], exec
	s_cselect_b32 s13, s15, s21
	s_cselect_b32 s70, s14, s20
	s_ashr_i32 s11, s10, 31
	s_lshl_b64 s[16:17], s[10:11], 19
	v_readlane_b32 s22, v255, 5
	v_readlane_b32 s23, v255, 6
	s_add_u32 s16, s22, s16
	s_addc_u32 s17, s23, s17
	s_and_b64 s[22:23], s[4:5], exec
	s_cselect_b32 s11, s17, s19
	s_cselect_b32 s71, s16, s18
	s_add_u32 s72, s18, 0x100
	s_addc_u32 s73, s19, 0
	s_add_u32 s18, s20, 0x40080
	v_mov_b32_e32 v0, 0
	s_addc_u32 s19, s21, 0
	s_mov_b32 s75, -2
	v_mov_b32_e32 v1, v0
	v_mov_b32_e32 v2, v0
	v_mov_b32_e32 v3, v0
	v_mov_b32_e32 v4, v0
	v_mov_b32_e32 v5, v0
	v_mov_b32_e32 v6, v0
	v_mov_b32_e32 v7, v0
	v_mov_b32_e32 v16, v0
	v_mov_b32_e32 v17, v0
	v_mov_b32_e32 v18, v0
	v_mov_b32_e32 v19, v0
	v_mov_b32_e32 v20, v0
	v_mov_b32_e32 v21, v0
	v_mov_b32_e32 v22, v0
	v_mov_b32_e32 v23, v0
	v_mov_b32_e32 v34, v0
	v_mov_b32_e32 v35, v0
	v_mov_b32_e32 v36, v0
	v_mov_b32_e32 v37, v0
	v_mov_b32_e32 v38, v0
	v_mov_b32_e32 v39, v0
	v_mov_b32_e32 v40, v0
	v_mov_b32_e32 v41, v0
	v_mov_b32_e32 v50, v0
	v_mov_b32_e32 v51, v0
	v_mov_b32_e32 v52, v0
	v_mov_b32_e32 v53, v0
	v_mov_b32_e32 v54, v0
	v_mov_b32_e32 v55, v0
	v_mov_b32_e32 v56, v0
	v_mov_b32_e32 v57, v0
	v_mov_b32_e32 v8, v0
	v_mov_b32_e32 v9, v0
	v_mov_b32_e32 v10, v0
	v_mov_b32_e32 v11, v0
	v_mov_b32_e32 v12, v0
	v_mov_b32_e32 v13, v0
	v_mov_b32_e32 v14, v0
	v_mov_b32_e32 v15, v0
	v_mov_b32_e32 v24, v0
	v_mov_b32_e32 v25, v0
	v_mov_b32_e32 v26, v0
	v_mov_b32_e32 v27, v0
	v_mov_b32_e32 v28, v0
	v_mov_b32_e32 v29, v0
	v_mov_b32_e32 v30, v0
	v_mov_b32_e32 v31, v0
	v_mov_b32_e32 v42, v0
	v_mov_b32_e32 v43, v0
	v_mov_b32_e32 v44, v0
	v_mov_b32_e32 v45, v0
	v_mov_b32_e32 v46, v0
	v_mov_b32_e32 v47, v0
	v_mov_b32_e32 v48, v0
	v_mov_b32_e32 v49, v0
	v_mov_b32_e32 v58, v0
	v_mov_b32_e32 v59, v0
	v_mov_b32_e32 v60, v0
	v_mov_b32_e32 v61, v0
	v_mov_b32_e32 v62, v0
	v_mov_b32_e32 v63, v0
	v_mov_b32_e32 v64, v0
	v_mov_b32_e32 v65, v0
	v_mov_b32_e32 v66, v0
	v_mov_b32_e32 v67, v0
	v_mov_b32_e32 v68, v0
	v_mov_b32_e32 v69, v0
	v_mov_b32_e32 v70, v0
	v_mov_b32_e32 v71, v0
	v_mov_b32_e32 v72, v0
	v_mov_b32_e32 v73, v0
	v_mov_b32_e32 v82, v0
	v_mov_b32_e32 v83, v0
	v_mov_b32_e32 v84, v0
	v_mov_b32_e32 v85, v0
	v_mov_b32_e32 v86, v0
	v_mov_b32_e32 v87, v0
	v_mov_b32_e32 v88, v0
	v_mov_b32_e32 v89, v0
	v_mov_b32_e32 v98, v0
	v_mov_b32_e32 v99, v0
	v_mov_b32_e32 v100, v0
	v_mov_b32_e32 v101, v0
	v_mov_b32_e32 v102, v0
	v_mov_b32_e32 v103, v0
	v_mov_b32_e32 v104, v0
	v_mov_b32_e32 v105, v0
	v_mov_b32_e32 v114, v0
	v_mov_b32_e32 v115, v0
	v_mov_b32_e32 v116, v0
	v_mov_b32_e32 v117, v0
	v_mov_b32_e32 v118, v0
	v_mov_b32_e32 v119, v0
	v_mov_b32_e32 v120, v0
	v_mov_b32_e32 v121, v0
	v_mov_b32_e32 v74, v0
	v_mov_b32_e32 v75, v0
	v_mov_b32_e32 v76, v0
	v_mov_b32_e32 v77, v0
	v_mov_b32_e32 v78, v0
	v_mov_b32_e32 v79, v0
	v_mov_b32_e32 v80, v0
	v_mov_b32_e32 v81, v0
	v_mov_b32_e32 v90, v0
	v_mov_b32_e32 v91, v0
	v_mov_b32_e32 v92, v0
	v_mov_b32_e32 v93, v0
	v_mov_b32_e32 v94, v0
	v_mov_b32_e32 v95, v0
	v_mov_b32_e32 v96, v0
	v_mov_b32_e32 v97, v0
	v_mov_b32_e32 v106, v0
	v_mov_b32_e32 v107, v0
	v_mov_b32_e32 v108, v0
	v_mov_b32_e32 v109, v0
	v_mov_b32_e32 v110, v0
	v_mov_b32_e32 v111, v0
	v_mov_b32_e32 v112, v0
	v_mov_b32_e32 v113, v0
	v_mov_b32_e32 v122, v0
	v_mov_b32_e32 v123, v0
	v_mov_b32_e32 v124, v0
	v_mov_b32_e32 v125, v0
	v_mov_b32_e32 v126, v0
	v_mov_b32_e32 v127, v0
	v_mov_b32_e32 v128, v0
	v_mov_b32_e32 v129, v0
	s_cmp_eq_u64 s[6:7], 0
	s_cbranch_scc1 .Lprio_214
	s_setprio 1

; template <class Epi>
; __device__ __forceinline__ void gemm_phase(LAS unsigned char* lds, const Gemm g, const StaticOrder& S, const Epi& E) {
;     ...
;         const bool has_next = S.next(ui + 1, nxt);
;         const char* nA = has_next ? (const char*)g.A + (size_t)nxt.pm * tstepA : cA; const char* nB = has_next ? (const char*)g.Bt + (size_t)nxt.pn * tstepB : cB;
;         for (int t = 0; t < nt; t += 2) {
;     ...
; #pragma unroll
;         for (int a = 0; a < 2; ++a)
; #pragma unroll
;             for (int b = 0; b < 2; ++b)
; #pragma unroll
;                 for (int m = 0; m < 4; ++m)
; #pragma unroll
;                     for (int n = 0; n < 2; ++n) acc[a][b][m][n] = (f32x4){0.f, 0.f, 0.f, 0.f};
;         cur = nxt; cA = nA; cB = nB; ++ui;
.LBB0_563:
	s_add_u32 s30, s26, 0x100
	s_addc_u32 s31, s27, 0
	s_add_u32 s26, s28, 0x80
	v_mov_b32_e32 v0, 0
	s_addc_u32 s27, s29, 0
	s_mov_b32 s28, 0
	v_mov_b32_e32 v1, v0
	v_mov_b32_e32 v2, v0
	v_mov_b32_e32 v3, v0
	v_mov_b32_e32 v4, v0
	v_mov_b32_e32 v5, v0
	v_mov_b32_e32 v6, v0
	v_mov_b32_e32 v7, v0
	v_mov_b32_e32 v16, v0
	v_mov_b32_e32 v17, v0
	v_mov_b32_e32 v18, v0
	v_mov_b32_e32 v19, v0
	v_mov_b32_e32 v20, v0
	v_mov_b32_e32 v21, v0
	v_mov_b32_e32 v22, v0
	v_mov_b32_e32 v23, v0
	v_mov_b32_e32 v34, v0
	v_mov_b32_e32 v35, v0
	v_mov_b32_e32 v36, v0
	v_mov_b32_e32 v37, v0
	v_mov_b32_e32 v38, v0
	v_mov_b32_e32 v39, v0
	v_mov_b32_e32 v40, v0
	v_mov_b32_e32 v41, v0
	v_mov_b32_e32 v50, v0
	v_mov_b32_e32 v51, v0
	v_mov_b32_e32 v52, v0
	v_mov_b32_e32 v53, v0
	v_mov_b32_e32 v54, v0
	v_mov_b32_e32 v55, v0
	v_mov_b32_e32 v56, v0
	v_mov_b32_e32 v57, v0
	v_mov_b32_e32 v8, v0
	v_mov_b32_e32 v9, v0
	v_mov_b32_e32 v10, v0
	v_mov_b32_e32 v11, v0
	v_mov_b32_e32 v12, v0
	v_mov_b32_e32 v13, v0
	v_mov_b32_e32 v14, v0
	v_mov_b32_e32 v15, v0
	v_mov_b32_e32 v24, v0
	v_mov_b32_e32 v25, v0
	v_mov_b32_e32 v26, v0
	v_mov_b32_e32 v27, v0
	v_mov_b32_e32 v28, v0
	v_mov_b32_e32 v29, v0
	v_mov_b32_e32 v30, v0
	v_mov_b32_e32 v31, v0
	v_mov_b32_e32 v42, v0
	v_mov_b32_e32 v43, v0
	v_mov_b32_e32 v44, v0
	v_mov_b32_e32 v45, v0
	v_mov_b32_e32 v46, v0
	v_mov_b32_e32 v47, v0
	v_mov_b32_e32 v48, v0
	v_mov_b32_e32 v49, v0
	v_mov_b32_e32 v58, v0
	v_mov_b32_e32 v59, v0
	v_mov_b32_e32 v60, v0
	v_mov_b32_e32 v61, v0
	v_mov_b32_e32 v62, v0
	v_mov_b32_e32 v63, v0
	v_mov_b32_e32 v64, v0
	v_mov_b32_e32 v65, v0
	v_mov_b32_e32 v66, v0
	v_mov_b32_e32 v67, v0
	v_mov_b32_e32 v68, v0
	v_mov_b32_e32 v69, v0
	v_mov_b32_e32 v70, v0
	v_mov_b32_e32 v71, v0
	v_mov_b32_e32 v72, v0
	v_mov_b32_e32 v73, v0
	v_mov_b32_e32 v82, v0
	v_mov_b32_e32 v83, v0
	v_mov_b32_e32 v84, v0
	v_mov_b32_e32 v85, v0
	v_mov_b32_e32 v86, v0
	v_mov_b32_e32 v87, v0
	v_mov_b32_e32 v88, v0
	v_mov_b32_e32 v89, v0
	v_mov_b32_e32 v98, v0
	v_mov_b32_e32 v99, v0
	v_mov_b32_e32 v100, v0
	v_mov_b32_e32 v101, v0
	v_mov_b32_e32 v102, v0
	v_mov_b32_e32 v103, v0
	v_mov_b32_e32 v104, v0
	v_mov_b32_e32 v105, v0
	v_mov_b32_e32 v114, v0
	v_mov_b32_e32 v115, v0
	v_mov_b32_e32 v116, v0
	v_mov_b32_e32 v117, v0
	v_mov_b32_e32 v118, v0
	v_mov_b32_e32 v119, v0
	v_mov_b32_e32 v120, v0
	v_mov_b32_e32 v121, v0
	v_mov_b32_e32 v74, v0
	v_mov_b32_e32 v75, v0
	v_mov_b32_e32 v76, v0
	v_mov_b32_e32 v77, v0
	v_mov_b32_e32 v78, v0
	v_mov_b32_e32 v79, v0
	v_mov_b32_e32 v80, v0
	v_mov_b32_e32 v81, v0
	v_mov_b32_e32 v90, v0
	v_mov_b32_e32 v91, v0
	v_mov_b32_e32 v92, v0
	v_mov_b32_e32 v93, v0
	v_mov_b32_e32 v94, v0
	v_mov_b32_e32 v95, v0
	v_mov_b32_e32 v96, v0
	v_mov_b32_e32 v97, v0
	v_mov_b32_e32 v106, v0
	v_mov_b32_e32 v107, v0
	v_mov_b32_e32 v108, v0
	v_mov_b32_e32 v109, v0
	v_mov_b32_e32 v110, v0
	v_mov_b32_e32 v111, v0
	v_mov_b32_e32 v112, v0
	v_mov_b32_e32 v113, v0
	v_mov_b32_e32 v122, v0
	v_mov_b32_e32 v123, v0
	v_mov_b32_e32 v124, v0
	v_mov_b32_e32 v125, v0
	v_mov_b32_e32 v126, v0
	v_mov_b32_e32 v127, v0
	v_mov_b32_e32 v128, v0
	v_mov_b32_e32 v129, v0
	s_cmp_eq_u64 s[20:21], 0
	s_cbranch_scc1 .Lprio_564
	s_setprio 1

; template <class Epi>
; __device__ __forceinline__ void gemm_phase(LAS unsigned char* lds, const Gemm g, const StaticOrder& S, const Epi& E) {
;     ...
;         const bool has_next = S.next(ui + 1, nxt);
;         const char* nA = has_next ? (const char*)g.A + (size_t)nxt.pm * tstepA : cA; const char* nB = has_next ? (const char*)g.Bt + (size_t)nxt.pn * tstepB : cB;
;         for (int t = 0; t < nt; t += 2) {
;     ...
; #pragma unroll
;         for (int a = 0; a < 2; ++a)
; #pragma unroll
;             for (int b = 0; b < 2; ++b)
; #pragma unroll
;                 for (int m = 0; m < 4; ++m)
; #pragma unroll
;                     for (int n = 0; n < 2; ++n) acc[a][b][m][n] = (f32x4){0.f, 0.f, 0.f, 0.f};
;         cur = nxt; cA = nA; cB = nB; ++ui;
.LBB0_630:
	s_add_u32 s28, s22, 0x100
	s_addc_u32 s29, s23, 0
	s_add_u32 s22, s26, 0x80
	v_mov_b32_e32 v0, 0
	s_addc_u32 s23, s27, 0
	s_mov_b32 s26, 0
	v_mov_b32_e32 v1, v0
	v_mov_b32_e32 v2, v0
	v_mov_b32_e32 v3, v0
	v_mov_b32_e32 v4, v0
	v_mov_b32_e32 v5, v0
	v_mov_b32_e32 v6, v0
	v_mov_b32_e32 v7, v0
	v_mov_b32_e32 v16, v0
	v_mov_b32_e32 v17, v0
	v_mov_b32_e32 v18, v0
	v_mov_b32_e32 v19, v0
	v_mov_b32_e32 v20, v0
	v_mov_b32_e32 v21, v0
	v_mov_b32_e32 v22, v0
	v_mov_b32_e32 v23, v0
	v_mov_b32_e32 v34, v0
	v_mov_b32_e32 v35, v0
	v_mov_b32_e32 v36, v0
	v_mov_b32_e32 v37, v0
	v_mov_b32_e32 v38, v0
	v_mov_b32_e32 v39, v0
	v_mov_b32_e32 v40, v0
	v_mov_b32_e32 v41, v0
	v_mov_b32_e32 v50, v0
	v_mov_b32_e32 v51, v0
	v_mov_b32_e32 v52, v0
	v_mov_b32_e32 v53, v0
	v_mov_b32_e32 v54, v0
	v_mov_b32_e32 v55, v0
	v_mov_b32_e32 v56, v0
	v_mov_b32_e32 v57, v0
	v_mov_b32_e32 v8, v0
	v_mov_b32_e32 v9, v0
	v_mov_b32_e32 v10, v0
	v_mov_b32_e32 v11, v0
	v_mov_b32_e32 v12, v0
	v_mov_b32_e32 v13, v0
	v_mov_b32_e32 v14, v0
	v_mov_b32_e32 v15, v0
	v_mov_b32_e32 v24, v0
	v_mov_b32_e32 v25, v0
	v_mov_b32_e32 v26, v0
	v_mov_b32_e32 v27, v0
	v_mov_b32_e32 v28, v0
	v_mov_b32_e32 v29, v0
	v_mov_b32_e32 v30, v0
	v_mov_b32_e32 v31, v0
	v_mov_b32_e32 v42, v0
	v_mov_b32_e32 v43, v0
	v_mov_b32_e32 v44, v0
	v_mov_b32_e32 v45, v0
	v_mov_b32_e32 v46, v0
	v_mov_b32_e32 v47, v0
	v_mov_b32_e32 v48, v0
	v_mov_b32_e32 v49, v0
	v_mov_b32_e32 v58, v0
	v_mov_b32_e32 v59, v0
	v_mov_b32_e32 v60, v0
	v_mov_b32_e32 v61, v0
	v_mov_b32_e32 v62, v0
	v_mov_b32_e32 v63, v0
	v_mov_b32_e32 v64, v0
	v_mov_b32_e32 v65, v0
	v_mov_b32_e32 v66, v0
	v_mov_b32_e32 v67, v0
	v_mov_b32_e32 v68, v0
	v_mov_b32_e32 v69, v0
	v_mov_b32_e32 v70, v0
	v_mov_b32_e32 v71, v0
	v_mov_b32_e32 v72, v0
	v_mov_b32_e32 v73, v0
	v_mov_b32_e32 v82, v0
	v_mov_b32_e32 v83, v0
	v_mov_b32_e32 v84, v0
	v_mov_b32_e32 v85, v0
	v_mov_b32_e32 v86, v0
	v_mov_b32_e32 v87, v0
	v_mov_b32_e32 v88, v0
	v_mov_b32_e32 v89, v0
	v_mov_b32_e32 v98, v0
	v_mov_b32_e32 v99, v0
	v_mov_b32_e32 v100, v0
	v_mov_b32_e32 v101, v0
	v_mov_b32_e32 v102, v0
	v_mov_b32_e32 v103, v0
	v_mov_b32_e32 v104, v0
	v_mov_b32_e32 v105, v0
	v_mov_b32_e32 v114, v0
	v_mov_b32_e32 v115, v0
	v_mov_b32_e32 v116, v0
	v_mov_b32_e32 v117, v0
	v_mov_b32_e32 v118, v0
	v_mov_b32_e32 v119, v0
	v_mov_b32_e32 v120, v0
	v_mov_b32_e32 v121, v0
	v_mov_b32_e32 v74, v0
	v_mov_b32_e32 v75, v0
	v_mov_b32_e32 v76, v0
	v_mov_b32_e32 v77, v0
	v_mov_b32_e32 v78, v0
	v_mov_b32_e32 v79, v0
	v_mov_b32_e32 v80, v0
	v_mov_b32_e32 v81, v0
	v_mov_b32_e32 v90, v0
	v_mov_b32_e32 v91, v0
	v_mov_b32_e32 v92, v0
	v_mov_b32_e32 v93, v0
	v_mov_b32_e32 v94, v0
	v_mov_b32_e32 v95, v0
	v_mov_b32_e32 v96, v0
	v_mov_b32_e32 v97, v0
	v_mov_b32_e32 v106, v0
	v_mov_b32_e32 v107, v0
	v_mov_b32_e32 v108, v0
	v_mov_b32_e32 v109, v0
	v_mov_b32_e32 v110, v0
	v_mov_b32_e32 v111, v0
	v_mov_b32_e32 v112, v0
	v_mov_b32_e32 v113, v0
	v_mov_b32_e32 v122, v0
	v_mov_b32_e32 v123, v0
	v_mov_b32_e32 v124, v0
	v_mov_b32_e32 v125, v0
	v_mov_b32_e32 v126, v0
	v_mov_b32_e32 v127, v0
	v_mov_b32_e32 v128, v0
	v_mov_b32_e32 v129, v0
	s_cmp_eq_u64 s[18:19], 0
	s_cbranch_scc1 .Lprio_631
	s_setprio 1

; template <class Epi>
; __device__ __forceinline__ void gemm_phase(LAS unsigned char* lds, const Gemm g, const StaticOrder& S, const Epi& E) {
;     ...
;         const bool has_next = S.next(ui + 1, nxt);
;         const char* nA = has_next ? (const char*)g.A + (size_t)nxt.pm * tstepA : cA; const char* nB = has_next ? (const char*)g.Bt + (size_t)nxt.pn * tstepB : cB;
;         for (int t = 0; t < nt; t += 2) {
;     ...
; #pragma unroll
;         for (int a = 0; a < 2; ++a)
; #pragma unroll
;             for (int b = 0; b < 2; ++b)
; #pragma unroll
;                 for (int m = 0; m < 4; ++m)
; #pragma unroll
;                     for (int n = 0; n < 2; ++n) acc[a][b][m][n] = (f32x4){0.f, 0.f, 0.f, 0.f};
;         cur = nxt; cA = nA; cB = nB; ++ui;
.LBB0_698:
	s_add_u32 s75, s20, 0x100
	v_mov_b32_e32 v0, 0
	s_addc_u32 s76, s21, 0
	s_mov_b32 s78, -2
	v_mov_b32_e32 v1, v0
	v_mov_b32_e32 v2, v0
	v_mov_b32_e32 v3, v0
	v_mov_b32_e32 v4, v0
	v_mov_b32_e32 v5, v0
	v_mov_b32_e32 v6, v0
	v_mov_b32_e32 v7, v0
	v_mov_b32_e32 v16, v0
	v_mov_b32_e32 v17, v0
	v_mov_b32_e32 v18, v0
	v_mov_b32_e32 v19, v0
	v_mov_b32_e32 v20, v0
	v_mov_b32_e32 v21, v0
	v_mov_b32_e32 v22, v0
	v_mov_b32_e32 v23, v0
	v_mov_b32_e32 v34, v0
	v_mov_b32_e32 v35, v0
	v_mov_b32_e32 v36, v0
	v_mov_b32_e32 v37, v0
	v_mov_b32_e32 v38, v0
	v_mov_b32_e32 v39, v0
	v_mov_b32_e32 v40, v0
	v_mov_b32_e32 v41, v0
	v_mov_b32_e32 v50, v0
	v_mov_b32_e32 v51, v0
	v_mov_b32_e32 v52, v0
	v_mov_b32_e32 v53, v0
	v_mov_b32_e32 v54, v0
	v_mov_b32_e32 v55, v0
	v_mov_b32_e32 v56, v0
	v_mov_b32_e32 v57, v0
	v_mov_b32_e32 v8, v0
	v_mov_b32_e32 v9, v0
	v_mov_b32_e32 v10, v0
	v_mov_b32_e32 v11, v0
	v_mov_b32_e32 v12, v0
	v_mov_b32_e32 v13, v0
	v_mov_b32_e32 v14, v0
	v_mov_b32_e32 v15, v0
	v_mov_b32_e32 v24, v0
	v_mov_b32_e32 v25, v0
	v_mov_b32_e32 v26, v0
	v_mov_b32_e32 v27, v0
	v_mov_b32_e32 v28, v0
	v_mov_b32_e32 v29, v0
	v_mov_b32_e32 v30, v0
	v_mov_b32_e32 v31, v0
	v_mov_b32_e32 v42, v0
	v_mov_b32_e32 v43, v0
	v_mov_b32_e32 v44, v0
	v_mov_b32_e32 v45, v0
	v_mov_b32_e32 v46, v0
	v_mov_b32_e32 v47, v0
	v_mov_b32_e32 v48, v0
	v_mov_b32_e32 v49, v0
	v_mov_b32_e32 v58, v0
	v_mov_b32_e32 v59, v0
	v_mov_b32_e32 v60, v0
	v_mov_b32_e32 v61, v0
	v_mov_b32_e32 v62, v0
	v_mov_b32_e32 v63, v0
	v_mov_b32_e32 v64, v0
	v_mov_b32_e32 v65, v0
	v_mov_b32_e32 v66, v0
	v_mov_b32_e32 v67, v0
	v_mov_b32_e32 v68, v0
	v_mov_b32_e32 v69, v0
	v_mov_b32_e32 v70, v0
	v_mov_b32_e32 v71, v0
	v_mov_b32_e32 v72, v0
	v_mov_b32_e32 v73, v0
	v_mov_b32_e32 v82, v0
	v_mov_b32_e32 v83, v0
	v_mov_b32_e32 v84, v0
	v_mov_b32_e32 v85, v0
	v_mov_b32_e32 v86, v0
	v_mov_b32_e32 v87, v0
	v_mov_b32_e32 v88, v0
	v_mov_b32_e32 v89, v0
	v_mov_b32_e32 v98, v0
	v_mov_b32_e32 v99, v0
	v_mov_b32_e32 v100, v0
	v_mov_b32_e32 v101, v0
	v_mov_b32_e32 v102, v0
	v_mov_b32_e32 v103, v0
	v_mov_b32_e32 v104, v0
	v_mov_b32_e32 v105, v0
	v_mov_b32_e32 v114, v0
	v_mov_b32_e32 v115, v0
	v_mov_b32_e32 v116, v0
	v_mov_b32_e32 v117, v0
	v_mov_b32_e32 v118, v0
	v_mov_b32_e32 v119, v0
	v_mov_b32_e32 v120, v0
	v_mov_b32_e32 v121, v0
	v_mov_b32_e32 v74, v0
	v_mov_b32_e32 v75, v0
	v_mov_b32_e32 v76, v0
	v_mov_b32_e32 v77, v0
	v_mov_b32_e32 v78, v0
	v_mov_b32_e32 v79, v0
	v_mov_b32_e32 v80, v0
	v_mov_b32_e32 v81, v0
	v_mov_b32_e32 v90, v0
	v_mov_b32_e32 v91, v0
	v_mov_b32_e32 v92, v0
	v_mov_b32_e32 v93, v0
	v_mov_b32_e32 v94, v0
	v_mov_b32_e32 v95, v0
	v_mov_b32_e32 v96, v0
	v_mov_b32_e32 v97, v0
	v_mov_b32_e32 v106, v0
	v_mov_b32_e32 v107, v0
	v_mov_b32_e32 v108, v0
	v_mov_b32_e32 v109, v0
	v_mov_b32_e32 v110, v0
	v_mov_b32_e32 v111, v0
	v_mov_b32_e32 v112, v0
	v_mov_b32_e32 v113, v0
	v_mov_b32_e32 v122, v0
	v_mov_b32_e32 v123, v0
	v_mov_b32_e32 v124, v0
	v_mov_b32_e32 v125, v0
	v_mov_b32_e32 v126, v0
	v_mov_b32_e32 v127, v0
	v_mov_b32_e32 v128, v0
	v_mov_b32_e32 v129, v0
	s_cmp_eq_u64 s[14:15], 0
	s_cbranch_scc1 .Lprio_699
	s_setprio 1

; template <class Epi>
; __device__ __forceinline__ void gemm_phase(LAS unsigned char* lds, const Gemm g, const StaticOrder& S, const Epi& E) {
;     ...
;         const bool has_next = S.next(ui + 1, nxt);
;         const char* nA = has_next ? (const char*)g.A + (size_t)nxt.pm * tstepA : cA; const char* nB = has_next ? (const char*)g.Bt + (size_t)nxt.pn * tstepB : cB;
;         for (int t = 0; t < nt; t += 2) {
;     ...
; #pragma unroll
;         for (int a = 0; a < 2; ++a)
; #pragma unroll
;             for (int b = 0; b < 2; ++b)
; #pragma unroll
;                 for (int m = 0; m < 4; ++m)
; #pragma unroll
;                     for (int n = 0; n < 2; ++n) acc[a][b][m][n] = (f32x4){0.f, 0.f, 0.f, 0.f};
;         cur = nxt; cA = nA; cB = nB; ++ui;
.LBB0_752:
	s_ashr_i32 s11, s10, 31
	s_lshl_b64 s[12:13], s[10:11], 19
	s_add_u32 s12, s84, s12
	s_addc_u32 s13, s85, s13
	s_and_b64 s[14:15], s[4:5], exec
	s_cselect_b32 s11, s13, s21
	s_cselect_b32 s68, s12, s20
	s_ashr_i32 s9, s8, 31
	s_lshl_b64 s[14:15], s[8:9], 19
	s_add_u32 s14, s24, s14
	s_addc_u32 s15, s26, s15
	s_and_b64 s[22:23], s[4:5], exec
	s_cselect_b32 s9, s15, s19
	s_cselect_b32 s69, s14, s18
	s_add_u32 s70, s18, 0x100
	s_addc_u32 s71, s19, 0
	s_add_u32 s18, s20, 0x40080
	v_mov_b32_e32 v0, 0
	s_addc_u32 s19, s21, 0
	s_mov_b32 s72, -2
	v_mov_b32_e32 v1, v0
	v_mov_b32_e32 v2, v0
	v_mov_b32_e32 v3, v0
	v_mov_b32_e32 v8, v0
	v_mov_b32_e32 v9, v0
	v_mov_b32_e32 v10, v0
	v_mov_b32_e32 v11, v0
	v_mov_b32_e32 v16, v0
	v_mov_b32_e32 v17, v0
	v_mov_b32_e32 v18, v0
	v_mov_b32_e32 v19, v0
	v_mov_b32_e32 v24, v0
	v_mov_b32_e32 v25, v0
	v_mov_b32_e32 v26, v0
	v_mov_b32_e32 v27, v0
	v_mov_b32_e32 v34, v0
	v_mov_b32_e32 v35, v0
	v_mov_b32_e32 v36, v0
	v_mov_b32_e32 v37, v0
	v_mov_b32_e32 v42, v0
	v_mov_b32_e32 v43, v0
	v_mov_b32_e32 v44, v0
	v_mov_b32_e32 v45, v0
	v_mov_b32_e32 v50, v0
	v_mov_b32_e32 v51, v0
	v_mov_b32_e32 v52, v0
	v_mov_b32_e32 v53, v0
	v_mov_b32_e32 v58, v0
	v_mov_b32_e32 v59, v0
	v_mov_b32_e32 v60, v0
	v_mov_b32_e32 v61, v0
	v_mov_b32_e32 v4, v0
	v_mov_b32_e32 v5, v0
	v_mov_b32_e32 v6, v0
	v_mov_b32_e32 v7, v0
	v_mov_b32_e32 v12, v0
	v_mov_b32_e32 v13, v0
	v_mov_b32_e32 v14, v0
	v_mov_b32_e32 v15, v0
	v_mov_b32_e32 v20, v0
	v_mov_b32_e32 v21, v0
	v_mov_b32_e32 v22, v0
	v_mov_b32_e32 v23, v0
	v_mov_b32_e32 v28, v0
	v_mov_b32_e32 v29, v0
	v_mov_b32_e32 v30, v0
	v_mov_b32_e32 v31, v0
	v_mov_b32_e32 v38, v0
	v_mov_b32_e32 v39, v0
	v_mov_b32_e32 v40, v0
	v_mov_b32_e32 v41, v0
	v_mov_b32_e32 v46, v0
	v_mov_b32_e32 v47, v0
	v_mov_b32_e32 v48, v0
	v_mov_b32_e32 v49, v0
	v_mov_b32_e32 v54, v0
	v_mov_b32_e32 v55, v0
	v_mov_b32_e32 v56, v0
	v_mov_b32_e32 v57, v0
	v_mov_b32_e32 v62, v0
	v_mov_b32_e32 v63, v0
	v_mov_b32_e32 v64, v0
	v_mov_b32_e32 v65, v0
	v_mov_b32_e32 v66, v0
	v_mov_b32_e32 v67, v0
	v_mov_b32_e32 v68, v0
	v_mov_b32_e32 v69, v0
	v_mov_b32_e32 v74, v0
	v_mov_b32_e32 v75, v0
	v_mov_b32_e32 v76, v0
	v_mov_b32_e32 v77, v0
	v_mov_b32_e32 v82, v0
	v_mov_b32_e32 v83, v0
	v_mov_b32_e32 v84, v0
	v_mov_b32_e32 v85, v0
	v_mov_b32_e32 v90, v0
	v_mov_b32_e32 v91, v0
	v_mov_b32_e32 v92, v0
	v_mov_b32_e32 v93, v0
	v_mov_b32_e32 v98, v0
	v_mov_b32_e32 v99, v0
	v_mov_b32_e32 v100, v0
	v_mov_b32_e32 v101, v0
	v_mov_b32_e32 v106, v0
	v_mov_b32_e32 v107, v0
	v_mov_b32_e32 v108, v0
	v_mov_b32_e32 v109, v0
	v_mov_b32_e32 v114, v0
	v_mov_b32_e32 v115, v0
	v_mov_b32_e32 v116, v0
	v_mov_b32_e32 v117, v0
	v_mov_b32_e32 v122, v0
	v_mov_b32_e32 v123, v0
	v_mov_b32_e32 v124, v0
	v_mov_b32_e32 v125, v0
	v_mov_b32_e32 v70, v0
	v_mov_b32_e32 v71, v0
	v_mov_b32_e32 v72, v0
	v_mov_b32_e32 v73, v0
	v_mov_b32_e32 v78, v0
	v_mov_b32_e32 v79, v0
	v_mov_b32_e32 v80, v0
	v_mov_b32_e32 v81, v0
	v_mov_b32_e32 v86, v0
	v_mov_b32_e32 v87, v0
	v_mov_b32_e32 v88, v0
	v_mov_b32_e32 v89, v0
	v_mov_b32_e32 v94, v0
	v_mov_b32_e32 v95, v0
	v_mov_b32_e32 v96, v0
	v_mov_b32_e32 v97, v0
	v_mov_b32_e32 v102, v0
	v_mov_b32_e32 v103, v0
	v_mov_b32_e32 v104, v0
	v_mov_b32_e32 v105, v0
	v_mov_b32_e32 v110, v0
	v_mov_b32_e32 v111, v0
	v_mov_b32_e32 v112, v0
	v_mov_b32_e32 v113, v0
	v_mov_b32_e32 v118, v0
	v_mov_b32_e32 v119, v0
	v_mov_b32_e32 v120, v0
	v_mov_b32_e32 v121, v0
	v_mov_b32_e32 v126, v0
	v_mov_b32_e32 v127, v0
	v_mov_b32_e32 v128, v0
	v_mov_b32_e32 v129, v0
	s_cmp_eq_u64 s[6:7], 0
	s_cbranch_scc1 .Lprio_753
	s_setprio 1

; template <class Epi>
; __device__ __forceinline__ void gemm_phase(LAS unsigned char* lds, const Gemm g, const StaticOrder& S, const Epi& E) {
;     ...
;         const bool has_next = S.next(ui + 1, nxt);
;         const char* nA = has_next ? (const char*)g.A + (size_t)nxt.pm * tstepA : cA; const char* nB = has_next ? (const char*)g.Bt + (size_t)nxt.pn * tstepB : cB;
;         for (int t = 0; t < nt; t += 2) {
;     ...
; #pragma unroll
;         for (int a = 0; a < 2; ++a)
; #pragma unroll
;             for (int b = 0; b < 2; ++b)
; #pragma unroll
;                 for (int m = 0; m < 4; ++m)
; #pragma unroll
;                     for (int n = 0; n < 2; ++n) acc[a][b][m][n] = (f32x4){0.f, 0.f, 0.f, 0.f};
;         cur = nxt; cA = nA; cB = nB; ++ui;
.LBB0_915:
	s_ashr_i32 s19, s18, 31
	s_lshl_b64 s[20:21], s[18:19], 19
	s_add_u32 s20, s84, s20
	s_addc_u32 s21, s85, s21
	s_and_b64 s[22:23], s[6:7], exec
	s_cselect_b32 s19, s21, s31
	s_cselect_b32 s27, s20, s30
	s_ashr_i32 s17, s16, 31
	s_lshl_b64 s[22:23], s[16:17], 19
	s_add_u32 s22, s35, s22
	s_addc_u32 s23, s3, s23
	s_and_b64 s[68:69], s[6:7], exec
	s_cselect_b32 s17, s23, s29
	s_cselect_b32 s94, s22, s28
	s_add_u32 s95, s28, 0x100
	s_addc_u32 s96, s29, 0
	s_add_u32 s28, s30, 0x40080
	v_mov_b32_e32 v0, 0
	s_addc_u32 s29, s31, 0
	s_mov_b32 s97, -2
	v_mov_b32_e32 v1, v0
	v_mov_b32_e32 v2, v0
	v_mov_b32_e32 v3, v0
	v_mov_b32_e32 v4, v0
	v_mov_b32_e32 v5, v0
	v_mov_b32_e32 v6, v0
	v_mov_b32_e32 v7, v0
	v_mov_b32_e32 v16, v0
	v_mov_b32_e32 v17, v0
	v_mov_b32_e32 v18, v0
	v_mov_b32_e32 v19, v0
	v_mov_b32_e32 v20, v0
	v_mov_b32_e32 v21, v0
	v_mov_b32_e32 v22, v0
	v_mov_b32_e32 v23, v0
	v_mov_b32_e32 v34, v0
	v_mov_b32_e32 v35, v0
	v_mov_b32_e32 v36, v0
	v_mov_b32_e32 v37, v0
	v_mov_b32_e32 v38, v0
	v_mov_b32_e32 v39, v0
	v_mov_b32_e32 v40, v0
	v_mov_b32_e32 v41, v0
	v_mov_b32_e32 v50, v0
	v_mov_b32_e32 v51, v0
	v_mov_b32_e32 v52, v0
	v_mov_b32_e32 v53, v0
	v_mov_b32_e32 v54, v0
	v_mov_b32_e32 v55, v0
	v_mov_b32_e32 v56, v0
	v_mov_b32_e32 v57, v0
	v_mov_b32_e32 v8, v0
	v_mov_b32_e32 v9, v0
	v_mov_b32_e32 v10, v0
	v_mov_b32_e32 v11, v0
	v_mov_b32_e32 v12, v0
	v_mov_b32_e32 v13, v0
	v_mov_b32_e32 v14, v0
	v_mov_b32_e32 v15, v0
	v_mov_b32_e32 v24, v0
	v_mov_b32_e32 v25, v0
	v_mov_b32_e32 v26, v0
	v_mov_b32_e32 v27, v0
	v_mov_b32_e32 v28, v0
	v_mov_b32_e32 v29, v0
	v_mov_b32_e32 v30, v0
	v_mov_b32_e32 v31, v0
	v_mov_b32_e32 v42, v0
	v_mov_b32_e32 v43, v0
	v_mov_b32_e32 v44, v0
	v_mov_b32_e32 v45, v0
	v_mov_b32_e32 v46, v0
	v_mov_b32_e32 v47, v0
	v_mov_b32_e32 v48, v0
	v_mov_b32_e32 v49, v0
	v_mov_b32_e32 v58, v0
	v_mov_b32_e32 v59, v0
	v_mov_b32_e32 v60, v0
	v_mov_b32_e32 v61, v0
	v_mov_b32_e32 v62, v0
	v_mov_b32_e32 v63, v0
	v_mov_b32_e32 v64, v0
	v_mov_b32_e32 v65, v0
	v_mov_b32_e32 v66, v0
	v_mov_b32_e32 v67, v0
	v_mov_b32_e32 v68, v0
	v_mov_b32_e32 v69, v0
	v_mov_b32_e32 v70, v0
	v_mov_b32_e32 v71, v0
	v_mov_b32_e32 v72, v0
	v_mov_b32_e32 v73, v0
	v_mov_b32_e32 v82, v0
	v_mov_b32_e32 v83, v0
	v_mov_b32_e32 v84, v0
	v_mov_b32_e32 v85, v0
	v_mov_b32_e32 v86, v0
	v_mov_b32_e32 v87, v0
	v_mov_b32_e32 v88, v0
	v_mov_b32_e32 v89, v0
	v_mov_b32_e32 v98, v0
	v_mov_b32_e32 v99, v0
	v_mov_b32_e32 v100, v0
	v_mov_b32_e32 v101, v0
	v_mov_b32_e32 v102, v0
	v_mov_b32_e32 v103, v0
	v_mov_b32_e32 v104, v0
	v_mov_b32_e32 v105, v0
	v_mov_b32_e32 v114, v0
	v_mov_b32_e32 v115, v0
	v_mov_b32_e32 v116, v0
	v_mov_b32_e32 v117, v0
	v_mov_b32_e32 v118, v0
	v_mov_b32_e32 v119, v0
	v_mov_b32_e32 v120, v0
	v_mov_b32_e32 v121, v0
	v_mov_b32_e32 v74, v0
	v_mov_b32_e32 v75, v0
	v_mov_b32_e32 v76, v0
	v_mov_b32_e32 v77, v0
	v_mov_b32_e32 v78, v0
	v_mov_b32_e32 v79, v0
	v_mov_b32_e32 v80, v0
	v_mov_b32_e32 v81, v0
	v_mov_b32_e32 v90, v0
	v_mov_b32_e32 v91, v0
	v_mov_b32_e32 v92, v0
	v_mov_b32_e32 v93, v0
	v_mov_b32_e32 v94, v0
	v_mov_b32_e32 v95, v0
	v_mov_b32_e32 v96, v0
	v_mov_b32_e32 v97, v0
	v_mov_b32_e32 v106, v0
	v_mov_b32_e32 v107, v0
	v_mov_b32_e32 v108, v0
	v_mov_b32_e32 v109, v0
	v_mov_b32_e32 v110, v0
	v_mov_b32_e32 v111, v0
	v_mov_b32_e32 v112, v0
	v_mov_b32_e32 v113, v0
	v_mov_b32_e32 v122, v0
	v_mov_b32_e32 v123, v0
	v_mov_b32_e32 v124, v0
	v_mov_b32_e32 v125, v0
	v_mov_b32_e32 v126, v0
	v_mov_b32_e32 v127, v0
	v_mov_b32_e32 v128, v0
	v_mov_b32_e32 v129, v0
	s_cmp_eq_u64 s[10:11], 0
	s_cbranch_scc1 .Lprio_916
	s_setprio 1
